# dense attention: next unit's Q fragments and K/V tiles 0,1 prefetched before the drain/finalize of the current unit (section 7.10), on top of v69
# speedup vs baseline: 1.0121x; 1.0121x over previous
.LBB0_1010:
	s_or_b64 exec, exec, s[46:47]
	s_and_b64 vcc, exec, s[38:39]
	s_waitcnt lgkmcnt(0)
	s_barrier
	s_cbranch_vccnz .LBB0_1016
	v_bfe_u32 v0, v5, 5, 1
	v_and_b32_e32 v202, 31, v5
	v_ashrrev_i32_e32 v5, 3, v5
	s_movk_i32 s5, 0x90
	v_lshlrev_b32_e32 v32, 3, v0
	v_lshlrev_b32_e32 v0, 4, v0
	v_mov_b32_e32 v1, v33
	v_mul_lo_u32 v6, v5, s5
	v_and_b32_e32 v7, 0x70, v4
	s_and_b32 s38, s4, 0xffffffc0
	v_lshl_add_u64 v[2:3], s[44:45], 0, v[0:1]
	s_mov_b64 s[4:5], 0xa000000
	v_lshl_add_u64 v[204:205], v[2:3], 0, s[4:5]
	v_lshl_or_b32 v2, v5, 13, v7
	v_mov_b32_e32 v5, v33
	v_mov_b32_e32 v3, v33
	v_lshl_add_u64 v[4:5], s[0:1], 0, v[4:5]
	s_mov_b64 s[0:1], 0xe800000
	v_add3_u32 v203, v6, v7, 0
	v_mul_u32_u24_e32 v1, 0x90, v202
	v_lshl_add_u64 v[6:7], s[42:43], 0, v[32:33]
	s_mov_b64 s[4:5], 0x11800000
	v_lshl_add_u64 v[208:209], v[4:5], 0, s[0:1]
	v_lshl_add_u64 v[2:3], s[40:41], 0, v[2:3]
	s_mov_b64 s[0:1], 0x10000000
	v_lshl_add_u64 v[206:207], v[6:7], 0, s[4:5]
	v_lshl_add_u64 v[210:211], v[2:3], 0, s[0:1]
	v_add3_u32 v32, 0, v0, v1
	v_add3_u32 v245, 0, v1, v0
	s_mov_b32 s100, 0
	s_mov_b32 s0, s2
.LBB0_1012:
	s_ashr_i32 s39, s0, 7
	s_lshl_b32 s4, s0, 9
	s_bfe_u32 s1, s0, 0x40003
	s_and_b32 s40, s4, 0xe00
	s_lshl_b32 s4, s39, 4
	s_or_b32 s4, s4, s1
	s_add_i32 s40, s40, s38
	s_ashr_i32 s5, s4, 31
	s_lshr_b32 s6, s0, 3
	s_lshl_b64 s[4:5], s[4:5], 12
	s_ashr_i32 s7, s40, 31
	s_add_u32 s4, s4, s40
	s_addc_u32 s5, s5, s7
	v_mov_b32_e32 v1, s5
	v_or_b32_e32 v0, s4, v202
	s_bfe_u32 s4, s6, 0x20002
	s_lshl_b32 s5, s39, 2
	s_or_b32 s4, s4, s5
	v_lshlrev_b64 v[0:1], 7, v[0:1]
	s_ashr_i32 s5, s4, 31
	v_lshl_add_u64 v[2:3], v[204:205], 0, v[0:1]
	v_or_b32_e32 v0, 0x1000, v0
	s_lshl_b64 s[4:5], s[4:5], 19
	v_lshl_add_u64 v[0:1], v[204:205], 0, v[0:1]
	v_lshl_add_u64 v[212:213], v[208:209], 0, s[4:5]
	v_lshl_add_u64 v[214:215], v[210:211], 0, s[4:5]
	s_cmp_eq_u32 s100, 0
	s_cbranch_scc0 .Lupf_h
	global_load_dwordx4 v[130:133], v[2:3], off
	global_load_dwordx4 v[134:137], v[2:3], off offset:32
	global_load_dwordx4 v[138:141], v[2:3], off offset:64
	global_load_dwordx4 v[142:145], v[2:3], off offset:96
	global_load_dwordx4 v[146:149], v[0:1], off
	global_load_dwordx4 v[150:153], v[0:1], off offset:32
	global_load_dwordx4 v[154:157], v[0:1], off offset:64
	global_load_dwordx4 v[158:161], v[0:1], off offset:96
	global_load_dwordx4 v[226:229], v[212:213], off
	global_load_dwordx4 v[230:233], v[214:215], off
	s_mov_b64 s[6:7], 0x2000
	v_lshl_add_u64 v[182:183], v[212:213], 0, s[6:7]
	global_load_dwordx4 v[182:185], v[182:183], off
	global_load_dwordx4 v[178:181], v[214:215], off offset:128
.Lupf_h:
	v_mov_b32_e32 v82, 0xf149f2ca
	s_mov_b32 s4, 0
	s_movk_i32 s42, 0x6c00
	s_movk_i32 s41, 0x4800
	s_mov_b32 s5, 0x9000
	v_mov_b32_e32 v162, 0
	v_mov_b32_e32 v163, 0
	v_mov_b32_e32 v164, 0
	v_mov_b32_e32 v165, 0
	v_mov_b32_e32 v174, 0
	v_mov_b32_e32 v175, 0
	v_mov_b32_e32 v176, 0
	v_mov_b32_e32 v177, 0
	v_mov_b32_e32 v166, 0
	v_mov_b32_e32 v167, 0
	v_mov_b32_e32 v168, 0
	v_mov_b32_e32 v169, 0
	v_mov_b32_e32 v170, 0
	v_mov_b32_e32 v171, 0
	v_mov_b32_e32 v172, 0
	v_mov_b32_e32 v173, 0
	v_mov_b32_e32 v83, v82
	v_mov_b32_e32 v84, v82
	v_mov_b32_e32 v85, v82
	v_mov_b32_e32 v86, v82
	v_mov_b32_e32 v87, v82
	v_mov_b32_e32 v88, v82
	v_mov_b32_e32 v89, v82
	v_mov_b32_e32 v90, v82
	v_mov_b32_e32 v91, v82
	v_mov_b32_e32 v92, v82
	v_mov_b32_e32 v93, v82
	v_mov_b32_e32 v94, v82
	v_mov_b32_e32 v95, v82
	v_mov_b32_e32 v96, v82
	v_mov_b32_e32 v97, v82
	v_mov_b32_e32 v66, v82
	v_mov_b32_e32 v67, v82
	v_mov_b32_e32 v68, v82
	v_mov_b32_e32 v69, v82
	v_mov_b32_e32 v70, v82
	v_mov_b32_e32 v71, v82
	v_mov_b32_e32 v72, v82
	v_mov_b32_e32 v73, v82
	v_mov_b32_e32 v74, v82
	v_mov_b32_e32 v75, v82
	v_mov_b32_e32 v76, v82
	v_mov_b32_e32 v77, v82
	v_mov_b32_e32 v78, v82
	v_mov_b32_e32 v79, v82
	v_mov_b32_e32 v80, v82
	v_mov_b32_e32 v81, v82
	s_cmp_eq_u32 s100, 0
	s_cbranch_scc0 .Lupf_w
	s_waitcnt vmcnt(3)
	ds_write_b128 v203, v[226:229]
	s_waitcnt vmcnt(2)
	s_branch .Lupf_w2
.Lupf_w:
	s_waitcnt vmcnt(11)
	ds_write_b128 v203, v[226:229]
	s_waitcnt vmcnt(10)
	s_mov_b32 s100, 0
.Lupf_w2:
	ds_write_b128 v203, v[230:233] offset:18432
	v_mov_b32_e32 v0, 0
	v_mov_b32_e32 v1, v0
	v_mov_b32_e32 v2, v0
	v_mov_b32_e32 v3, v0
	v_mov_b32_e32 v4, v0
	v_mov_b32_e32 v5, v0
	v_mov_b32_e32 v6, v0
	v_mov_b32_e32 v7, v0
	v_mov_b32_e32 v8, v0
	v_mov_b32_e32 v9, v0
	v_mov_b32_e32 v10, v0
	v_mov_b32_e32 v11, v0
	v_mov_b32_e32 v12, v0
	v_mov_b32_e32 v13, v0
	v_mov_b32_e32 v14, v0
	v_mov_b32_e32 v15, v0
	v_mov_b32_e32 v16, v0
	v_mov_b32_e32 v17, v0
	v_mov_b32_e32 v18, v0
	v_mov_b32_e32 v19, v0
	v_mov_b32_e32 v20, v0
	v_mov_b32_e32 v21, v0
	v_mov_b32_e32 v22, v0
	v_mov_b32_e32 v23, v0
	v_mov_b32_e32 v24, v0
	v_mov_b32_e32 v25, v0
	v_mov_b32_e32 v26, v0
	v_mov_b32_e32 v27, v0
	v_mov_b32_e32 v28, v0
	v_mov_b32_e32 v29, v0
	v_mov_b32_e32 v30, v0
	v_mov_b32_e32 v31, v0
	v_mov_b32_e32 v34, v0
	v_mov_b32_e32 v35, v0
	v_mov_b32_e32 v36, v0
	v_mov_b32_e32 v37, v0
	v_mov_b32_e32 v38, v0
	v_mov_b32_e32 v39, v0
	v_mov_b32_e32 v40, v0
	v_mov_b32_e32 v41, v0
	v_mov_b32_e32 v42, v0
	v_mov_b32_e32 v43, v0
	v_mov_b32_e32 v44, v0
	v_mov_b32_e32 v45, v0
	v_mov_b32_e32 v46, v0
	v_mov_b32_e32 v47, v0
	v_mov_b32_e32 v48, v0
	v_mov_b32_e32 v49, v0
	v_mov_b32_e32 v50, v0
	v_mov_b32_e32 v51, v0
	v_mov_b32_e32 v52, v0
	v_mov_b32_e32 v53, v0
	v_mov_b32_e32 v54, v0
	v_mov_b32_e32 v55, v0
	v_mov_b32_e32 v56, v0
	v_mov_b32_e32 v57, v0
	v_mov_b32_e32 v58, v0
	v_mov_b32_e32 v59, v0
	v_mov_b32_e32 v60, v0
	v_mov_b32_e32 v61, v0
	v_mov_b32_e32 v62, v0
	v_mov_b32_e32 v63, v0
	v_mov_b32_e32 v64, v0
	v_mov_b32_e32 v65, v0
	v_mov_b32_e32 v216, v0
	v_mov_b32_e32 v217, v0
	s_waitcnt lgkmcnt(0)
	s_barrier
	v_mov_b32_e32 v234, v245
	v_add_u32_e32 v235, s5, v32
	s_cmpk_lt_u32 s38, 0x100
	s_cselect_b32 s101, 0, 1
	v_mov_b32_e32 v186, 0
	v_mov_b32_e32 v187, 0
	v_mov_b32_e32 v188, 0
	v_mov_b32_e32 v189, 0
	v_mov_b32_e32 v190, 0
	v_mov_b32_e32 v191, 0
	v_mov_b32_e32 v192, 0
	v_mov_b32_e32 v193, 0
	v_mov_b32_e32 v218, 0
	v_mov_b32_e32 v219, 0
	v_mov_b32_e32 v220, 0
	v_mov_b32_e32 v221, 0
	v_mov_b32_e32 v222, 0
	v_mov_b32_e32 v223, 0
	v_mov_b32_e32 v224, 0
	v_mov_b32_e32 v225, 0
	ds_read_b128 v[226:229], v235
	ds_read_b128 v[230:233], v235 offset:4608

.Lpp_nb_p2:
	s_add_i32 s44, s0, s78
	s_cmpk_gt_i32 s44, 0x3ff
	s_cbranch_scc1 .Lupf_skip
	s_ashr_i32 s41, s44, 7
	s_lshl_b32 s4, s44, 9
	s_bfe_u32 s42, s44, 0x40003
	s_and_b32 s43, s4, 0xe00
	s_lshl_b32 s4, s41, 4
	s_or_b32 s4, s4, s42
	s_add_i32 s43, s43, s38
	s_ashr_i32 s5, s4, 31
	s_lshr_b32 s6, s44, 3
	s_lshl_b64 s[4:5], s[4:5], 12
	s_ashr_i32 s7, s43, 31
	s_add_u32 s4, s4, s43
	s_addc_u32 s5, s5, s7
	v_mov_b32_e32 v199, s5
	v_or_b32_e32 v198, s4, v202
	s_bfe_u32 s4, s6, 0x20002
	s_lshl_b32 s5, s41, 2
	s_or_b32 s4, s4, s5
	v_lshlrev_b64 v[198:199], 7, v[198:199]
	s_ashr_i32 s5, s4, 31
	v_lshl_add_u64 v[234:235], v[204:205], 0, v[198:199]
	v_or_b32_e32 v198, 0x1000, v198
	s_lshl_b64 s[4:5], s[4:5], 19
	v_lshl_add_u64 v[198:199], v[204:205], 0, v[198:199]
	v_lshl_add_u64 v[212:213], v[208:209], 0, s[4:5]
	global_load_dwordx4 v[130:133], v[234:235], off
	global_load_dwordx4 v[134:137], v[234:235], off offset:32
	global_load_dwordx4 v[138:141], v[234:235], off offset:64
	global_load_dwordx4 v[142:145], v[234:235], off offset:96
	global_load_dwordx4 v[146:149], v[198:199], off
	global_load_dwordx4 v[150:153], v[198:199], off offset:32
	global_load_dwordx4 v[154:157], v[198:199], off offset:64
	global_load_dwordx4 v[158:161], v[198:199], off offset:96
	v_lshl_add_u64 v[214:215], v[210:211], 0, s[4:5]
	global_load_dwordx4 v[226:229], v[212:213], off
	global_load_dwordx4 v[230:233], v[214:215], off
	s_mov_b64 s[6:7], 0x2000
	v_lshl_add_u64 v[182:183], v[212:213], 0, s[6:7]
	global_load_dwordx4 v[182:185], v[182:183], off
	global_load_dwordx4 v[178:181], v[214:215], off offset:128
	s_mov_b32 s100, 1
